# adds swa_finalize gate matvec: 8 LDS row reads kept in flight instead of 15 dependent round trips per direction
# baseline (speedup 1.0000x reference)
; DI void swa_finalize(const P& p, char* smem, int vb, int nvb) {
;     ...
; #pragma unroll
;     for (int dr = 0; dr < 2; ++dr) {
;       f32x4v lg = *(const f32x4v*)(gbs + dr * 256 + lane * 4);
; #pragma unroll
;       for (int r4 = 0; r4 < 4; ++r4) {
;         const f32x4v zg = *(const f32x4v*)(sds + dr * 16 + r4 * 4);
;         lg += *(const f32x4v*)(w2s + (dr * 16 + r4 * 4 + 0) * 256 + lane * 4) * zg.x;
;         lg += *(const f32x4v*)(w2s + (dr * 16 + r4 * 4 + 1) * 256 + lane * 4) * zg.y;
;         lg += *(const f32x4v*)(w2s + (dr * 16 + r4 * 4 + 2) * 256 + lane * 4) * zg.z;
;         lg += *(const f32x4v*)(w2s + (dr * 16 + r4 * 4 + 3) * 256 + lane * 4) * zg.w;
;       }
;       f32x4v al;
;       al.x = __expf((fminf(lg.x, 0.f) - __logf(1.f + __expf(-fabsf(lg.x)))) * (1.f / 16.f));
;       al.y = __expf((fminf(lg.y, 0.f) - __logf(1.f + __expf(-fabsf(lg.y)))) * (1.f / 16.f));
;       al.z = __expf((fminf(lg.z, 0.f) - __logf(1.f + __expf(-fabsf(lg.z)))) * (1.f / 16.f));
;       al.w = __expf((fminf(lg.w, 0.f) - __logf(1.f + __expf(-fabsf(lg.w)))) * (1.f / 16.f));
.LBB0_603:
	s_or_b64 exec, exec, s[4:5]
	s_waitcnt lgkmcnt(0)
	s_waitcnt lgkmcnt(0)
	ds_read_b128 v[16:19], v56 offset:32768
	ds_read_b128 v[20:23], v56
	ds_read_b128 v[24:27], v54 offset:34816
	ds_read_b128 v[40:43], v54 offset:34832
	ds_read_b128 v[44:47], v54 offset:34848
	s_waitcnt vmcnt(5)
	ds_read_b128 v[48:51], v54 offset:34864
	ds_read_b128 v[224:227], v56 offset:1024
	ds_read_b128 v[228:231], v56 offset:2048
	ds_read_b128 v[232:235], v56 offset:3072
	ds_read_b128 v[236:239], v56 offset:4096
	ds_read_b128 v[240:243], v56 offset:5120
	ds_read_b128 v[244:247], v56 offset:6144
	ds_read_b128 v[248:251], v56 offset:7168
	ds_read_b128 v[252:255], v56 offset:8192
	s_mov_b32 s5, 0xbfb8aa3b
	s_waitcnt lgkmcnt(11)
	v_pk_fma_f32 v[20:21], v[20:21], v[24:25], v[16:17] op_sel_hi:[1,0,1]
	v_pk_fma_f32 v[22:23], v[22:23], v[24:25], v[18:19] op_sel_hi:[1,0,1]
	s_mov_b32 s4, 0xdaf2000
	v_mov_b32_e32 v29, 0
	s_waitcnt lgkmcnt(7)
	v_pk_fma_f32 v[22:23], v[24:25], v[226:227], v[22:23] op_sel:[1,0,0]
	v_pk_fma_f32 v[20:21], v[24:25], v[224:225], v[20:21] op_sel:[1,0,0]
	ds_read_b128 v[224:227], v56 offset:9216
	v_mov_b32_e32 v24, v27
	s_waitcnt lgkmcnt(7)
	v_pk_fma_f32 v[20:21], v[26:27], v[228:229], v[20:21] op_sel_hi:[0,1,1]
	v_pk_fma_f32 v[22:23], v[26:27], v[230:231], v[22:23] op_sel_hi:[0,1,1]
	ds_read_b128 v[228:231], v56 offset:10240
	s_waitcnt lgkmcnt(7)
	v_pk_fma_f32 v[22:23], v[24:25], v[234:235], v[22:23] op_sel_hi:[0,1,1]
	v_pk_fma_f32 v[20:21], v[24:25], v[232:233], v[20:21] op_sel_hi:[0,1,1]
	ds_read_b128 v[232:235], v56 offset:11264
	v_mov_b32_e32 v24, v43
	s_waitcnt lgkmcnt(7)
	v_pk_fma_f32 v[20:21], v[236:237], v[40:41], v[20:21] op_sel_hi:[1,0,1]
	v_pk_fma_f32 v[22:23], v[238:239], v[40:41], v[22:23] op_sel_hi:[1,0,1]
	ds_read_b128 v[236:239], v56 offset:12288
	s_waitcnt lgkmcnt(7)
	v_pk_fma_f32 v[22:23], v[40:41], v[242:243], v[22:23] op_sel:[1,0,0]
	v_pk_fma_f32 v[20:21], v[40:41], v[240:241], v[20:21] op_sel:[1,0,0]
	ds_read_b128 v[240:243], v56 offset:13312
	v_lshl_add_u64 v[40:41], s[70:71], 0, v[38:39]
	s_waitcnt lgkmcnt(7)
	v_pk_fma_f32 v[20:21], v[42:43], v[244:245], v[20:21] op_sel_hi:[0,1,1]
	v_pk_fma_f32 v[22:23], v[42:43], v[246:247], v[22:23] op_sel_hi:[0,1,1]
	ds_read_b128 v[244:247], v56 offset:14336
	s_waitcnt lgkmcnt(7)
	v_pk_fma_f32 v[22:23], v[24:25], v[250:251], v[22:23] op_sel_hi:[0,1,1]
	v_pk_fma_f32 v[20:21], v[24:25], v[248:249], v[20:21] op_sel_hi:[0,1,1]
	ds_read_b128 v[248:251], v56 offset:15360
	v_mov_b32_e32 v24, v47
	s_waitcnt lgkmcnt(7)
	v_pk_fma_f32 v[20:21], v[252:253], v[44:45], v[20:21] op_sel_hi:[1,0,1]
	v_pk_fma_f32 v[22:23], v[254:255], v[44:45], v[22:23] op_sel_hi:[1,0,1]
	s_waitcnt lgkmcnt(6)
	v_pk_fma_f32 v[22:23], v[44:45], v[226:227], v[22:23] op_sel:[1,0,0]
	v_pk_fma_f32 v[20:21], v[44:45], v[224:225], v[20:21] op_sel:[1,0,0]
	s_waitcnt lgkmcnt(5)
	v_pk_fma_f32 v[20:21], v[46:47], v[228:229], v[20:21] op_sel_hi:[0,1,1]
	v_pk_fma_f32 v[22:23], v[46:47], v[230:231], v[22:23] op_sel_hi:[0,1,1]
	s_waitcnt lgkmcnt(4)
	v_pk_fma_f32 v[22:23], v[24:25], v[234:235], v[22:23] op_sel_hi:[0,1,1]
	v_pk_fma_f32 v[20:21], v[24:25], v[232:233], v[20:21] op_sel_hi:[0,1,1]
	v_mov_b32_e32 v24, v51
	s_waitcnt lgkmcnt(3)
	v_pk_fma_f32 v[20:21], v[236:237], v[48:49], v[20:21] op_sel_hi:[1,0,1]
	v_pk_fma_f32 v[22:23], v[238:239], v[48:49], v[22:23] op_sel_hi:[1,0,1]
	s_waitcnt lgkmcnt(2)
	v_pk_fma_f32 v[22:23], v[48:49], v[242:243], v[22:23] op_sel:[1,0,0]
	v_pk_fma_f32 v[20:21], v[48:49], v[240:241], v[20:21] op_sel:[1,0,0]
	s_waitcnt lgkmcnt(1)
	v_pk_fma_f32 v[20:21], v[50:51], v[244:245], v[20:21] op_sel_hi:[0,1,1]
	v_pk_fma_f32 v[22:23], v[50:51], v[246:247], v[22:23] op_sel_hi:[0,1,1]
	s_waitcnt lgkmcnt(0)
	v_mov_b32_e32 v16, v248
	v_mov_b32_e32 v17, v249
	v_mov_b32_e32 v18, v250
	v_mov_b32_e32 v19, v251
	v_pk_fma_f32 v[16:17], v[24:25], v[16:17], v[20:21] op_sel_hi:[0,1,1]
	v_min_f32_e32 v20, 0, v16
	v_mul_f32_e64 v16, |v16|, s5
	v_exp_f32_e32 v16, v16
	v_pk_fma_f32 v[18:19], v[24:25], v[18:19], v[22:23] op_sel_hi:[0,1,1]
	v_add_f32_e32 v16, 1.0, v16
	v_cmp_gt_f32_e32 vcc, s9, v16
	s_nop 1
	v_cndmask_b32_e64 v21, 0, 32, vcc
	v_ldexp_f32 v16, v16, v21
	v_log_f32_e32 v16, v16
	s_nop 0
	v_mul_f32_e32 v21, 0x3f317217, v16
	v_fma_f32 v21, v16, s11, -v21
	v_fmac_f32_e32 v21, 0x3377d1cf, v16
	v_fmac_f32_e32 v21, 0x3f317217, v16
	v_cmp_lt_f32_e64 s[38:39], |v16|, s35
	s_nop 1
	v_cndmask_b32_e64 v16, v16, v21, s[38:39]
	v_cndmask_b32_e32 v21, 0, v147, vcc
	v_sub_f32_e32 v16, v16, v21
	v_sub_f32_e32 v16, v20, v16
	v_min_f32_e32 v20, 0, v17
	v_mul_f32_e64 v17, |v17|, s5
	v_exp_f32_e32 v17, v17
	v_mul_f32_e32 v16, 0x3d800000, v16
	v_mul_f32_e32 v16, 0x3fb8aa3b, v16
	v_exp_f32_e32 v16, v16
	v_add_f32_e32 v17, 1.0, v17
	v_cmp_gt_f32_e32 vcc, s9, v17
	s_nop 1
	v_cndmask_b32_e64 v21, 0, 32, vcc
	v_ldexp_f32 v17, v17, v21
	v_log_f32_e32 v17, v17
	s_nop 0
	v_mul_f32_e32 v21, 0x3f317217, v17
	v_fma_f32 v21, v17, s11, -v21
	v_fmac_f32_e32 v21, 0x3377d1cf, v17
	v_fmac_f32_e32 v21, 0x3f317217, v17
	v_cmp_lt_f32_e64 s[38:39], |v17|, s35
	s_nop 1
	v_cndmask_b32_e64 v17, v17, v21, s[38:39]
	v_cndmask_b32_e32 v21, 0, v147, vcc
	v_sub_f32_e32 v17, v17, v21
	v_sub_f32_e32 v17, v20, v17
	v_min_f32_e32 v20, 0, v18
	v_mul_f32_e64 v18, |v18|, s5
	v_exp_f32_e32 v18, v18
	v_mul_f32_e32 v17, 0x3d800000, v17
	v_mul_f32_e32 v17, 0x3fb8aa3b, v17
	v_exp_f32_e32 v17, v17
	v_add_f32_e32 v18, 1.0, v18
	v_cmp_gt_f32_e32 vcc, s9, v18
	s_nop 1
	v_cndmask_b32_e64 v21, 0, 32, vcc
	v_ldexp_f32 v18, v18, v21
	v_log_f32_e32 v18, v18
	s_nop 0
	v_mul_f32_e32 v21, 0x3f317217, v18
	v_fma_f32 v21, v18, s11, -v21
	v_fmac_f32_e32 v21, 0x3377d1cf, v18
; DI void swa_finalize(const P& p, char* smem, int vb, int nvb) {
;     ...
;     for (int dr = 0; dr < 2; ++dr) {
;       f32x4v lg = *(const f32x4v*)(gbs + dr * 256 + lane * 4);
; #pragma unroll
;       for (int r4 = 0; r4 < 4; ++r4) {
;         const f32x4v zg = *(const f32x4v*)(sds + dr * 16 + r4 * 4);
;         lg += *(const f32x4v*)(w2s + (dr * 16 + r4 * 4 + 0) * 256 + lane * 4) * zg.x;
;         lg += *(const f32x4v*)(w2s + (dr * 16 + r4 * 4 + 1) * 256 + lane * 4) * zg.y;
;         lg += *(const f32x4v*)(w2s + (dr * 16 + r4 * 4 + 2) * 256 + lane * 4) * zg.z;
;         lg += *(const f32x4v*)(w2s + (dr * 16 + r4 * 4 + 3) * 256 + lane * 4) * zg.w;
;       }
;       f32x4v al;
;       al.x = __expf((fminf(lg.x, 0.f) - __logf(1.f + __expf(-fabsf(lg.x)))) * (1.f / 16.f));
;       al.y = __expf((fminf(lg.y, 0.f) - __logf(1.f + __expf(-fabsf(lg.y)))) * (1.f / 16.f));
;       al.z = __expf((fminf(lg.z, 0.f) - __logf(1.f + __expf(-fabsf(lg.z)))) * (1.f / 16.f));
;       al.w = __expf((fminf(lg.w, 0.f) - __logf(1.f + __expf(-fabsf(lg.w)))) * (1.f / 16.f));
;       *(f32x4v*)((dr == 0 ? alpha0 : alpha1) + (size_t)t * 256 + lane * 4) = al;
	v_fmac_f32_e32 v21, 0x3f317217, v18
	v_cmp_lt_f32_e64 s[38:39], |v18|, s35
	s_nop 1
	v_cndmask_b32_e64 v18, v18, v21, s[38:39]
	v_cndmask_b32_e32 v21, 0, v147, vcc
	v_sub_f32_e32 v18, v18, v21
	v_sub_f32_e32 v18, v20, v18
	v_min_f32_e32 v20, 0, v19
	v_mul_f32_e64 v19, |v19|, s5
	v_exp_f32_e32 v19, v19
	v_mul_f32_e32 v18, 0x3d800000, v18
	v_mul_f32_e32 v18, 0x3fb8aa3b, v18
	v_exp_f32_e32 v18, v18
	v_add_f32_e32 v19, 1.0, v19
	v_cmp_gt_f32_e32 vcc, s9, v19
	s_nop 1
	v_cndmask_b32_e64 v21, 0, 32, vcc
	v_ldexp_f32 v19, v19, v21
	v_log_f32_e32 v19, v19
	s_nop 0
	v_mul_f32_e32 v21, 0x3f317217, v19
	v_fma_f32 v21, v19, s11, -v21
	v_fmac_f32_e32 v21, 0x3377d1cf, v19
	v_fmac_f32_e32 v21, 0x3f317217, v19
	v_cmp_lt_f32_e64 s[38:39], |v19|, s35
	s_nop 1
	v_cndmask_b32_e64 v19, v19, v21, s[38:39]
	v_cndmask_b32_e32 v21, 0, v147, vcc
	v_sub_f32_e32 v19, v19, v21
	v_sub_f32_e32 v19, v20, v19
	v_mul_f32_e32 v19, 0x3d800000, v19
	v_mul_f32_e32 v19, 0x3fb8aa3b, v19
	v_exp_f32_e32 v19, v19
	v_add_co_u32_e32 v20, vcc, s4, v40
	s_nop 1
	v_addc_co_u32_e32 v21, vcc, 0, v41, vcc
	global_store_dwordx4 v[20:21], v[16:19], off
	ds_read_b128 v[16:19], v56 offset:33792
	ds_read_b128 v[42:45], v56 offset:16384
	ds_read_b128 v[46:49], v54 offset:34880
	ds_read_b128 v[50:53], v54 offset:34896
	ds_read_b128 v[24:27], v54 offset:34912
	ds_read_b128 v[20:23], v54 offset:34928
	ds_read_b128 v[224:227], v56 offset:17408
	ds_read_b128 v[228:231], v56 offset:18432
	ds_read_b128 v[232:235], v56 offset:19456
	ds_read_b128 v[236:239], v56 offset:20480
	ds_read_b128 v[240:243], v56 offset:21504
	ds_read_b128 v[244:247], v56 offset:22528
	ds_read_b128 v[248:251], v56 offset:23552
	ds_read_b128 v[252:255], v56 offset:24576
	s_waitcnt lgkmcnt(11)
	v_pk_fma_f32 v[42:43], v[42:43], v[46:47], v[16:17] op_sel_hi:[1,0,1]
	v_pk_fma_f32 v[44:45], v[44:45], v[46:47], v[18:19] op_sel_hi:[1,0,1]
	s_waitcnt lgkmcnt(7)
	v_pk_fma_f32 v[44:45], v[46:47], v[226:227], v[44:45] op_sel:[1,0,0]
	v_pk_fma_f32 v[42:43], v[46:47], v[224:225], v[42:43] op_sel:[1,0,0]
	ds_read_b128 v[224:227], v56 offset:25600
	v_mov_b32_e32 v46, v49
	s_waitcnt lgkmcnt(7)
	v_pk_fma_f32 v[42:43], v[48:49], v[228:229], v[42:43] op_sel_hi:[0,1,1]
	v_pk_fma_f32 v[44:45], v[48:49], v[230:231], v[44:45] op_sel_hi:[0,1,1]
	ds_read_b128 v[228:231], v56 offset:26624
	s_waitcnt lgkmcnt(7)
	v_pk_fma_f32 v[44:45], v[46:47], v[234:235], v[44:45] op_sel_hi:[0,1,1]
	v_pk_fma_f32 v[42:43], v[46:47], v[232:233], v[42:43] op_sel_hi:[0,1,1]
	ds_read_b128 v[232:235], v56 offset:27648
	v_mov_b32_e32 v46, v53
	s_waitcnt lgkmcnt(7)
	v_pk_fma_f32 v[42:43], v[236:237], v[50:51], v[42:43] op_sel_hi:[1,0,1]
	v_pk_fma_f32 v[44:45], v[238:239], v[50:51], v[44:45] op_sel_hi:[1,0,1]
	ds_read_b128 v[236:239], v56 offset:28672
	s_waitcnt lgkmcnt(7)
	v_pk_fma_f32 v[44:45], v[50:51], v[242:243], v[44:45] op_sel:[1,0,0]
	v_pk_fma_f32 v[42:43], v[50:51], v[240:241], v[42:43] op_sel:[1,0,0]
	ds_read_b128 v[240:243], v56 offset:29696
	s_waitcnt lgkmcnt(7)
	v_pk_fma_f32 v[42:43], v[52:53], v[244:245], v[42:43] op_sel_hi:[0,1,1]
	v_pk_fma_f32 v[44:45], v[52:53], v[246:247], v[44:45] op_sel_hi:[0,1,1]
	ds_read_b128 v[244:247], v56 offset:30720
	s_waitcnt lgkmcnt(7)
	v_pk_fma_f32 v[44:45], v[46:47], v[250:251], v[44:45] op_sel_hi:[0,1,1]
	v_pk_fma_f32 v[42:43], v[46:47], v[248:249], v[42:43] op_sel_hi:[0,1,1]
	ds_read_b128 v[248:251], v56 offset:31744
	s_waitcnt lgkmcnt(7)
	v_pk_fma_f32 v[42:43], v[252:253], v[24:25], v[42:43] op_sel_hi:[1,0,1]
	v_pk_fma_f32 v[44:45], v[254:255], v[24:25], v[44:45] op_sel_hi:[1,0,1]
	s_waitcnt lgkmcnt(6)
	v_pk_fma_f32 v[44:45], v[24:25], v[226:227], v[44:45] op_sel:[1,0,0]
	v_pk_fma_f32 v[24:25], v[24:25], v[224:225], v[42:43] op_sel:[1,0,0]
	s_waitcnt lgkmcnt(5)
	v_pk_fma_f32 v[24:25], v[26:27], v[228:229], v[24:25] op_sel_hi:[0,1,1]
	v_pk_fma_f32 v[42:43], v[26:27], v[230:231], v[44:45] op_sel_hi:[0,1,1]
	v_mov_b32_e32 v26, v27
	s_waitcnt lgkmcnt(4)
	v_pk_fma_f32 v[42:43], v[26:27], v[234:235], v[42:43] op_sel_hi:[0,1,1]
	v_pk_fma_f32 v[24:25], v[26:27], v[232:233], v[24:25] op_sel_hi:[0,1,1]
	s_waitcnt lgkmcnt(3)
; DI void swa_finalize(const P& p, char* smem, int vb, int nvb) {
;     ...
;       f32x4v lg = *(const f32x4v*)(gbs + dr * 256 + lane * 4);
; #pragma unroll
;       for (int r4 = 0; r4 < 4; ++r4) {
;         const f32x4v zg = *(const f32x4v*)(sds + dr * 16 + r4 * 4);
;         lg += *(const f32x4v*)(w2s + (dr * 16 + r4 * 4 + 0) * 256 + lane * 4) * zg.x;
;         lg += *(const f32x4v*)(w2s + (dr * 16 + r4 * 4 + 1) * 256 + lane * 4) * zg.y;
;         lg += *(const f32x4v*)(w2s + (dr * 16 + r4 * 4 + 2) * 256 + lane * 4) * zg.z;
;         lg += *(const f32x4v*)(w2s + (dr * 16 + r4 * 4 + 3) * 256 + lane * 4) * zg.w;
;       }
;       f32x4v al;
;       al.x = __expf((fminf(lg.x, 0.f) - __logf(1.f + __expf(-fabsf(lg.x)))) * (1.f / 16.f));
;       al.y = __expf((fminf(lg.y, 0.f) - __logf(1.f + __expf(-fabsf(lg.y)))) * (1.f / 16.f));
;       al.z = __expf((fminf(lg.z, 0.f) - __logf(1.f + __expf(-fabsf(lg.z)))) * (1.f / 16.f));
;       al.w = __expf((fminf(lg.w, 0.f) - __logf(1.f + __expf(-fabsf(lg.w)))) * (1.f / 16.f));
;       *(f32x4v*)((dr == 0 ? alpha0 : alpha1) + (size_t)t * 256 + lane * 4) = al;
;     ...
;     const bool lat = t < LAT;
;     const int pos = t & 2047;
;     float cs = 1.f, sn = 0.f;
;     if (lat) {
;       const int fi = lane & 15;
;       const float inv = exp2f(-(float)fi * (13.287712379549449f / 16.f));
;       const float pc = (lane & 16) ? (float)(pos & 63) : (float)(pos >> 6);
;       float rev = pc * inv * 0.15915494309189535f;
;       rev -= floorf(rev);
;       cs = __builtin_amdgcn_cosf(rev);
;       sn = __builtin_amdgcn_sinf(rev);
	v_pk_fma_f32 v[24:25], v[236:237], v[20:21], v[24:25] op_sel_hi:[1,0,1]
	v_pk_fma_f32 v[26:27], v[238:239], v[20:21], v[42:43] op_sel_hi:[1,0,1]
	s_waitcnt lgkmcnt(2)
	v_pk_fma_f32 v[26:27], v[20:21], v[242:243], v[26:27] op_sel:[1,0,0]
	v_pk_fma_f32 v[20:21], v[20:21], v[240:241], v[24:25] op_sel:[1,0,0]
	s_waitcnt lgkmcnt(1)
	v_pk_fma_f32 v[20:21], v[22:23], v[244:245], v[20:21] op_sel_hi:[0,1,1]
	v_pk_fma_f32 v[24:25], v[22:23], v[246:247], v[26:27] op_sel_hi:[0,1,1]
	v_mov_b32_e32 v22, v23
	s_waitcnt lgkmcnt(0)
	v_mov_b32_e32 v16, v248
	v_mov_b32_e32 v17, v249
	v_mov_b32_e32 v18, v250
	v_mov_b32_e32 v19, v251
	v_pk_fma_f32 v[16:17], v[22:23], v[16:17], v[20:21] op_sel_hi:[0,1,1]
	v_min_f32_e32 v20, 0, v16
	v_mul_f32_e64 v16, |v16|, s5
	v_exp_f32_e32 v16, v16
	v_pk_fma_f32 v[18:19], v[22:23], v[18:19], v[24:25] op_sel_hi:[0,1,1]
	v_add_f32_e32 v16, 1.0, v16
	v_cmp_gt_f32_e32 vcc, s9, v16
	s_nop 1
	v_cndmask_b32_e64 v21, 0, 32, vcc
	v_ldexp_f32 v16, v16, v21
	v_log_f32_e32 v16, v16
	s_nop 0
	v_mul_f32_e32 v21, 0x3f317217, v16
	v_fma_f32 v21, v16, s11, -v21
	v_fmac_f32_e32 v21, 0x3377d1cf, v16
	v_fmac_f32_e32 v21, 0x3f317217, v16
	v_cmp_lt_f32_e64 s[38:39], |v16|, s35
	s_nop 1
	v_cndmask_b32_e64 v16, v16, v21, s[38:39]
	v_cndmask_b32_e32 v21, 0, v147, vcc
	v_sub_f32_e32 v16, v16, v21
	v_sub_f32_e32 v16, v20, v16
	v_min_f32_e32 v20, 0, v17
	v_mul_f32_e64 v17, |v17|, s5
	v_exp_f32_e32 v17, v17
	v_mul_f32_e32 v16, 0x3d800000, v16
	v_mul_f32_e32 v16, 0x3fb8aa3b, v16
	v_exp_f32_e32 v16, v16
	v_add_f32_e32 v17, 1.0, v17
	v_cmp_gt_f32_e32 vcc, s9, v17
	s_nop 1
	v_cndmask_b32_e64 v21, 0, 32, vcc
	v_ldexp_f32 v17, v17, v21
	v_log_f32_e32 v17, v17
	s_nop 0
	v_mul_f32_e32 v21, 0x3f317217, v17
	v_fma_f32 v21, v17, s11, -v21
	v_fmac_f32_e32 v21, 0x3377d1cf, v17
	v_fmac_f32_e32 v21, 0x3f317217, v17
	v_cmp_lt_f32_e64 s[38:39], |v17|, s35
	s_nop 1
	v_cndmask_b32_e64 v17, v17, v21, s[38:39]
	v_cndmask_b32_e32 v21, 0, v147, vcc
	v_sub_f32_e32 v17, v17, v21
	v_sub_f32_e32 v17, v20, v17
	v_min_f32_e32 v20, 0, v18
	v_mul_f32_e64 v18, |v18|, s5
	v_exp_f32_e32 v18, v18
	v_mul_f32_e32 v17, 0x3d800000, v17
	v_mul_f32_e32 v17, 0x3fb8aa3b, v17
	v_exp_f32_e32 v17, v17
	v_add_f32_e32 v18, 1.0, v18
	v_cmp_gt_f32_e32 vcc, s9, v18
	s_nop 1
	v_cndmask_b32_e64 v21, 0, 32, vcc
	v_ldexp_f32 v18, v18, v21
	v_log_f32_e32 v18, v18
	s_nop 0
	v_mul_f32_e32 v21, 0x3f317217, v18
	v_fma_f32 v21, v18, s11, -v21
	v_fmac_f32_e32 v21, 0x3377d1cf, v18
	v_fmac_f32_e32 v21, 0x3f317217, v18
	v_cmp_lt_f32_e64 s[38:39], |v18|, s35
	s_nop 1
	v_cndmask_b32_e64 v18, v18, v21, s[38:39]
	v_cndmask_b32_e32 v21, 0, v147, vcc
	v_sub_f32_e32 v18, v18, v21
	v_sub_f32_e32 v18, v20, v18
	v_min_f32_e32 v20, 0, v19
	v_mul_f32_e64 v19, |v19|, s5
	v_exp_f32_e32 v19, v19
	v_mul_f32_e32 v18, 0x3d800000, v18
	v_mul_f32_e32 v18, 0x3fb8aa3b, v18
	v_exp_f32_e32 v18, v18
	v_add_f32_e32 v19, 1.0, v19
	v_cmp_gt_f32_e32 vcc, s9, v19
	s_nop 1
	v_cndmask_b32_e64 v21, 0, 32, vcc
	v_ldexp_f32 v19, v19, v21
	v_log_f32_e32 v19, v19
	s_nop 0
	v_mul_f32_e32 v21, 0x3f317217, v19
	v_fma_f32 v21, v19, s11, -v21
	v_fmac_f32_e32 v21, 0x3377d1cf, v19
	v_fmac_f32_e32 v21, 0x3f317217, v19
	v_cmp_lt_f32_e64 s[38:39], |v19|, s35
	s_nop 1
	v_cndmask_b32_e64 v19, v19, v21, s[38:39]
	v_cndmask_b32_e32 v21, 0, v147, vcc
	v_sub_f32_e32 v19, v19, v21
	v_sub_f32_e32 v19, v20, v19
	v_mul_f32_e32 v19, 0x3d800000, v19
	v_mul_f32_e32 v19, 0x3fb8aa3b, v19
	v_exp_f32_e32 v19, v19
	v_add_co_u32_e32 v20, vcc, 0x4472000, v40
	v_cmp_gt_i32_e64 s[38:39], s8, v28
	s_nop 0
	v_addc_co_u32_e32 v21, vcc, 0, v41, vcc
	global_store_dwordx4 v[20:21], v[16:19], off
	s_waitcnt lgkmcnt(0)
	v_cmp_lt_i32_e32 vcc, s46, v28
	s_nop 0
	v_mov_b32_e32 v16, 1.0
	s_and_saveexec_b64 s[4:5], s[38:39]
	s_cbranch_execz .LBB0_605
	v_and_b32_e32 v16, 63, v28
	v_bfe_u32 v17, v28, 6, 5
	v_cndmask_b32_e64 v16, v16, v17, s[74:75]
	v_cvt_f32_ubyte0_e32 v16, v16
	v_mul_f32_e32 v16, v57, v16
	v_mul_f32_e32 v17, 0.15915494, v16
	v_floor_f32_e32 v17, v17
	v_fma_f32 v17, v16, 0.15915494, -v17
	v_cos_f32_e32 v16, v17
	v_sin_f32_e32 v29, v17
